# P4: WGs 0-127 only arrive at the round-4 barrier; WGs 128-255 start P4 ~7us late (their slack) so the two halves of an XCD run epilogues at different times
# baseline (speedup 1.0000x reference)
; #define PG8_STAGE(bufoff, gbase, voff) do { _Pragma("unroll") for (int _i = 0; _i < 2; ++_i) \
;         __builtin_amdgcn_global_load_lds((const unsigned*)((const char*)(gbase) + (voff)[_i]), (PG8_LAS unsigned*)(lds + (bufoff) + ldsw + _i * 8192), 16, 0, 0); } while (0)
; #define PG8_WAIT_V(n) asm volatile("s_waitcnt vmcnt(" #n ")" ::: "memory")
; #define PG8_BAR __builtin_amdgcn_s_barrier()
; template <class Epi, class Sched, bool ALIGN_EPI = false, bool SP2 = false>
; __device__ __forceinline__ void gemm_phase(PG8_LAS unsigned char* lds, const Gemm g, const Sched& S, const Epi& E) {
;     ...
;     for (int i = 0; i < 2; ++i) { int R, C; stage_rc(tid * 16 + i * 8192, R, C); const int Rb = Epi::PERM ? ((R & ~31) + perm32(R & 31)) : R;
;         voffA[i] = (unsigned)(R * K + C) * 2u; voffB[i] = (unsigned)(Rb * K + C) * 2u; }
;     const size_t kstep = (size_t)(BK * 2);
;     const size_t hstep = (size_t)HALF * K * 2;
;     const size_t tstep = 2 * hstep;
;     const unsigned ldsw = (unsigned)wid * 1024u;
;     const int aoff = lds_byte(wr * 64 + fr, fq * 8), boff = lds_byte(wc * 32 + fr, fq * 8);
;     ...
;     Unit cur, nxt; int ui = 0;
;     if (!S.next(0, cur)) return;
;     f32x4 acc[2][2][4][2];
; #pragma unroll
;     for (int a = 0; a < 2; ++a)
; #pragma unroll
;         for (int b = 0; b < 2; ++b)
; #pragma unroll
;             for (int m = 0; m < 4; ++m)
; #pragma unroll
;                 for (int n = 0; n < 2; ++n) acc[a][b][m][n] = (f32x4){0.f, 0.f, 0.f, 0.f};
;     bf16x8 At[4][2], B0[2][2], B1[2][2];
;     const char* cA = (const char*)g.A + (size_t)cur.pm * tstep; const char* cB = (const char*)g.Bt + (size_t)cur.pn * tstep;
;     S.a_ready(cur);
;     if constexpr (SP2) {
;         PG8_STAGE(PG8_SB(0, 0), cB, voffB); PG8_STAGE(PG8_SB(0, 1), cB + hstep, voffB); PG8_STAGE(PG8_SA(0, 0), cA, voffA); PG8_STAGE(PG8_SA(0, 1), cA + hstep, voffA);
;         if (wr == 1) PG8_BAR;
;         PG8_WAIT_V(2); PG8_BAR;
;         PG8_STAGE(PG8_SB(1, 0), cB + kstep, voffB); PG8_STAGE(PG8_SA(1, 0), cA + kstep, voffA); PG8_STAGE(PG8_SB(1, 1), cB + hstep + kstep, voffB);
;         PG8_WAIT_V(6); PG8_BAR;
.LBB0_826:
	s_or_b64 exec, exec, s[0:1]
	s_mov_b32 s100, 0
	v_writelane_b32 v255, s6, 16
	v_writelane_b32 v255, s7, 17
	v_writelane_b32 v255, s34, 18
	v_writelane_b32 v255, s35, 19
	v_writelane_b32 v255, s40, 20
	v_writelane_b32 v255, s41, 21
	v_writelane_b32 v255, s42, 22
	v_writelane_b32 v255, s43, 23
	v_writelane_b32 v255, s70, 24
	v_writelane_b32 v255, s72, 25
	v_writelane_b32 v255, s84, 26
	v_writelane_b32 v255, s85, 27
	s_cmpk_lt_u32 s3, 0x80
	s_cbranch_scc1 .Lb3_nodelay
	s_sleep 127
	s_sleep 127
.Lb3_nodelay:
.Lb3_p4_top:
	s_add_u32 s10, s50, 0xf000000
	s_addc_u32 s11, s51, 0
	v_mov_b32_e32 v11, v234
	s_waitcnt lgkmcnt(0)
	s_barrier
	s_cmpk_lt_i32 s3, 0x480
	s_nop 0
	v_readfirstlane_b32 s1, v11
	s_cbranch_scc0 .LBB0_855
	v_lshlrev_b32_e32 v0, 4, v11
	v_add_u32_e32 v1, 0x2000, v0
	v_ashrrev_i32_e32 v2, 31, v1
	v_lshrrev_b32_e32 v2, 22, v2
	v_add_u32_e32 v2, v1, v2
	v_ashrrev_i32_e32 v8, 10, v2
	v_mul_i32_i24_e32 v2, 0x400, v8
	v_sub_u32_e32 v1, v1, v2
	v_lshrrev_b32_e32 v2, 4, v1
	v_bitop3_b32 v1, v2, v1, 32 bitop3:0x6c
	v_ashrrev_i32_e32 v2, 31, v1
	v_lshrrev_b32_e32 v2, 26, v2
	v_add_u32_e32 v2, v1, v2
	v_lshlrev_b32_e32 v3, 3, v8
	v_ashrrev_i32_e32 v9, 6, v2
	v_and_b32_e32 v3, -16, v3
	v_add_u32_e32 v3, v9, v3
	v_and_b32_e32 v4, 3, v9
	s_mov_b32 s0, 0x1fffe0
	v_lshrrev_b32_e32 v5, 2, v3
	v_lshlrev_b32_e32 v6, 1, v3
	v_and_b32_e32 v2, 0xc0, v2
	v_and_or_b32 v4, v3, s0, v4
	v_and_b32_e32 v5, 4, v5
	v_and_b32_e32 v6, 24, v6
	v_sub_u32_e32 v1, v1, v2
	v_mov_b32_e32 v2, 1
	v_or3_b32 v4, v4, v5, v6
	v_lshlrev_b32_e32 v5, 5, v8
	v_ashrrev_i16_sdwa v1, v2, sext(v1) dst_sel:DWORD dst_unused:UNUSED_PAD src0_sel:DWORD src1_sel:BYTE_0
	v_and_b32_e32 v5, 32, v5
	v_bfe_i32 v10, v1, 0, 16
	v_add_lshl_u32 v1, v5, v10, 1
	v_lshl_add_u32 v132, v4, 11, v1
	v_lshl_add_u32 v134, v3, 11, v1
	v_bfe_i32 v1, v11, 27, 1
	v_lshrrev_b32_e32 v1, 22, v1
	v_add_u32_e32 v1, v0, v1
	v_and_b32_e32 v1, 0xfffffc00, v1
	v_sub_u32_e32 v0, v0, v1
	v_lshrrev_b32_e32 v1, 4, v0
	v_ashrrev_i32_e32 v3, 31, v11
	v_bitop3_b32 v0, v1, v0, 32 bitop3:0x6c
	v_lshrrev_b32_e32 v3, 26, v3
	v_ashrrev_i32_e32 v1, 31, v0
	v_add_u32_e32 v3, v11, v3
	v_lshrrev_b32_e32 v1, 26, v1
	v_ashrrev_i32_e32 v13, 6, v3
	v_add_u32_e32 v1, v0, v1
	v_lshlrev_b32_e32 v3, 3, v13
	v_ashrrev_i32_e32 v12, 6, v1
	v_and_b32_e32 v3, -16, v3
	v_add_u32_e32 v3, v12, v3
	v_and_b32_e32 v4, 3, v12
	v_and_or_b32 v4, v3, s0, v4
	s_lshr_b32 s0, s93, 29
	s_add_i32 s0, s3, s0
	s_ashr_i32 s2, s1, 6
	s_ashr_i32 s4, s0, 3
	s_and_b32 s0, s0, -8
	s_ashr_i32 s12, s1, 8
	s_lshl_b32 s22, s2, 10
	s_sub_i32 s0, s3, s0
	s_cmp_lt_i32 s0, 0
	s_movk_i32 s23, 0x91
	s_cselect_b32 s5, s23, 0x90
	s_mul_i32 s0, s0, s5
	s_add_i32 s0, s0, s4
	s_mul_hi_i32 s4, s0, 0x38e38e39
	s_lshr_b32 s5, s4, 31
	s_ashr_i32 s4, s4, 4
	s_add_i32 s4, s4, s5
	s_lshl_b32 s5, s4, 3
	s_mulk_i32 s4, 0x48
	s_sub_i32 s4, s0, s4
	s_bfe_i32 s0, s4, 0x80000
	s_bfe_u32 s0, s0, 0x3000c
	s_add_i32 s8, s4, s0
	s_bfe_i32 s0, s8, 0x80000
	s_and_b32 s8, s8, 0xf8
	s_sub_i32 s4, s4, s8
	s_sext_i32_i16 s0, s0
	s_sext_i32_i8 s4, s4
	v_lshrrev_b32_e32 v5, 2, v3
	v_lshlrev_b32_e32 v6, 1, v3
	v_and_b32_e32 v1, 0xc0, v1
	s_lshr_b32 s0, s0, 3
	s_add_i32 s4, s5, s4
	v_and_b32_e32 v5, 4, v5
	v_and_b32_e32 v6, 24, v6
	v_sub_u32_e32 v0, v0, v1
	s_ashr_i32 s5, s4, 31
	s_bfe_i64 s[8:9], s[0:1], 0x100000
	v_or3_b32 v4, v4, v5, v6
	v_lshlrev_b32_e32 v5, 5, v13
	v_ashrrev_i16_sdwa v0, v2, sext(v0) dst_sel:DWORD dst_unused:UNUSED_PAD src0_sel:DWORD src1_sel:BYTE_0
	s_lshl_b64 s[14:15], s[4:5], 19
	s_lshl_b64 s[8:9], s[8:9], 19
	v_and_b32_e32 v5, 32, v5
	v_bfe_i32 v14, v0, 0, 16
	s_add_u32 s8, s42, s8
	v_add_lshl_u32 v0, v5, v14, 1
	s_addc_u32 s9, s43, s9
	s_add_i32 s30, s22, 0
	v_lshl_add_u32 v136, v4, 11, v0
	s_add_i32 m0, s30, 0x10000
	v_lshl_add_u32 v138, v3, 11, v0
	global_load_lds_dwordx4 v136, s[8:9]
	s_add_i32 m0, s30, 0x12000
	s_add_u32 s16, s8, 0x40000
	global_load_lds_dwordx4 v132, s[8:9]
	s_addc_u32 s17, s9, 0
	s_add_i32 m0, s30, 0x14000
	v_mov_b32_e32 v141, 0
	global_load_lds_dwordx4 v136, s[16:17]
	s_add_i32 m0, s30, 0x16000
	s_add_u32 s78, s40, s14
	s_addc_u32 s79, s41, s15
	s_add_i32 s31, s30, 0x2000
	global_load_lds_dwordx4 v132, s[16:17]
	s_mov_b32 m0, s30
	s_add_u32 s14, s78, 0x40000
	global_load_lds_dwordx4 v138, s[78:79]
	s_mov_b32 m0, s31
	s_addc_u32 s15, s79, 0
	s_add_i32 s33, s30, 0x4000
	global_load_lds_dwordx4 v134, s[78:79]
	s_mov_b32 m0, s33
	s_add_i32 s53, s30, 0x6000
	global_load_lds_dwordx4 v138, s[14:15]
	s_mov_b32 m0, s53
	v_mov_b32_e32 v137, v141
	global_load_lds_dwordx4 v134, s[14:15]
	v_mov_b32_e32 v133, v141
	v_mov_b32_e32 v139, v141
	v_mov_b32_e32 v135, v141
	s_cmp_eq_u32 s12, 1
	s_mov_b32 s13, 0
	v_lshl_add_u64 v[6:7], s[8:9], 0, v[136:137]
	v_lshl_add_u64 v[2:3], s[8:9], 0, v[132:133]
	v_lshl_add_u64 v[0:1], s[78:79], 0, v[138:139]
	s_cselect_b64 s[14:15], -1, 0
	v_lshl_add_u64 v[4:5], s[78:79], 0, v[134:135]
	s_add_u32 s5, s50, 0x1100500
	s_addc_u32 s44, s51, 0
	s_add_u32 s16, s50, 0x1100400
	s_mov_b64 s[18:19], 0x80
	s_addc_u32 s17, s51, 0
	s_and_b32 s59, s2, 3
	s_add_i32 m0, s30, 0x18000
	v_lshl_add_u64 v[6:7], v[6:7], 0, s[18:19]
	s_lshl_b32 s45, s12, 13
	s_lshl_b32 s46, s59, 12
	global_load_lds_dwordx4 v[6:7], off
	v_lshl_add_u64 v[2:3], v[2:3], 0, s[18:19]
	s_add_i32 m0, s30, 0x1a000
	s_add_i32 s61, s30, 0x8000
	s_add_i32 s69, s30, 0xa000
	global_load_lds_dwordx4 v[2:3], off
	v_lshl_add_u64 v[0:1], v[0:1], 0, s[18:19]
	s_mov_b32 m0, s61
	s_add_u32 s20, s8, 0x40080
	global_load_lds_dwordx4 v[0:1], off
	v_lshl_add_u64 v[0:1], v[4:5], 0, s[18:19]
	s_mov_b32 m0, s69
	s_addc_u32 s21, s9, 0
	global_load_lds_dwordx4 v[0:1], off
	s_add_i32 m0, s30, 0x1c000
	v_lshl_add_u64 v[0:1], s[20:21], 0, v[136:137]
	global_load_lds_dwordx4 v[0:1], off
	v_lshl_add_u64 v[0:1], s[20:21], 0, v[132:133]
	s_add_i32 m0, s30, 0x1e000
	s_or_b32 s86, s59, 0xffffffec
	global_load_lds_dwordx4 v[0:1], off
	s_cmp_lg_u32 s12, 1
	s_cbranch_scc1 .LBB0_829
	s_barrier
